# dn_prep: conv weights (item-invariant) for the next item are issued at step 5 of the current item, only the first item loads them at its top
# baseline (speedup 1.0000x reference)
; DI void unpack8(u32x4 w, float* f) { f[0] = bflo(w.x); f[1] = bfhi(w.x); f[2] = bflo(w.y); f[3] = bfhi(w.y); f[4] = bflo(w.z); f[5] = bfhi(w.z); f[6] = bflo(w.w); f[7] = bfhi(w.w); }
; DI void dn_prep_item(const Params& p, int l, int item, int next_item, u32x4 (&pre)[12], unsigned char* lds, int tid) {
;     ...
;         for (int mat = 0; mat < 3; ++mat) { const int col = mat * 512 + h * 64 + d0; float a[8];
; #pragma unroll
;             for (int e = 0; e < 8; ++e) a[e] = 0.f;
; #pragma unroll
;             for (int j = 0; j < 4; ++j) { const int t = n * 64 + i - 3 + j;
;                 if (t >= 0) { float xv[8]; unpack8(pre[mat * 4 + j], xv);
;                     const f32x4 w0 = *(const f32x4*)(cw + j * 1536 + col), w1 = *(const f32x4*)(cw + j * 1536 + col + 4);
; #pragma unroll
;                     for (int e = 0; e < 4; ++e) { a[e] += w0[e] * xv[e]; a[4 + e] += w1[e] * xv[4 + e]; } } }
;     ...
;     if (tid < 64) {
;         const float a = da_raw + dtb, bb = db_raw;
;         const float sp = (a > 20.f) ? a : ((a < -15.f) ? expf(a) : logf(1.f + expf(a)));
;         float x = -expf(alog) * sp;
.LBB0_285:
	s_or_b64 exec, exec, s[10:11]
	v_lshlrev_b32_e32 v56, 3, v54
	s_mul_i32 s5, s20, 0x6000
	v_ashrrev_i32_e32 v77, 3, v54
	v_and_b32_e32 v82, 56, v56
	s_waitcnt lgkmcnt(0)
	s_add_u32 s8, s8, s5
	s_mul_hi_i32 s5, s20, 0x6000
	v_add_u32_e32 v83, v1, v77
	v_lshlrev_b32_e32 v1, 2, v82
	s_addc_u32 s9, s9, s5
	v_lshl_or_b32 v164, s4, 8, v1
	v_lshl_add_u64 v[56:57], s[8:9], 0, v[164:165]
	s_mov_b64 s[22:23], 0x3000
	v_lshl_add_u64 v[190:191], v[56:57], 0, s[22:23]
	s_mov_b64 s[22:23], 0x1000
	v_lshl_add_u64 v[192:193], v[56:57], 0, s[22:23]
	s_mov_b64 s[22:23], 0x4000
	v_lshl_add_u64 v[194:195], v[56:57], 0, s[22:23]
	s_mov_b64 s[22:23], 0x2000
	v_lshl_add_u64 v[196:197], v[56:57], 0, s[22:23]
	s_mov_b64 s[22:23], 0x5000
	v_lshl_add_u64 v[198:199], v[56:57], 0, s[22:23]
	s_cmp_lg_u32 s42, s28
	s_cbranch_scc1 .Lcw_have
	global_load_dwordx4 v[88:91], v[56:57], off offset:16
	global_load_dwordx4 v[92:95], v[56:57], off
	global_load_dwordx4 v[96:99], v[190:191], off
	global_load_dwordx4 v[100:103], v[190:191], off offset:16
	global_load_dwordx4 v[104:107], v[192:193], off offset:2048
	global_load_dwordx4 v[108:111], v[192:193], off offset:2064
	global_load_dwordx4 v[112:115], v[194:195], off offset:2048
	global_load_dwordx4 v[116:119], v[194:195], off offset:2064
	global_load_dwordx4 v[120:123], v[56:57], off offset:2064
	global_load_dwordx4 v[124:127], v[56:57], off offset:2048
	global_load_dwordx4 v[128:131], v[190:191], off offset:2048
	global_load_dwordx4 v[132:135], v[190:191], off offset:2064
	global_load_dwordx4 v[136:139], v[196:197], off
	global_load_dwordx4 v[140:143], v[196:197], off offset:16
	global_load_dwordx4 v[144:147], v[198:199], off
	global_load_dwordx4 v[148:151], v[198:199], off offset:16
	global_load_dwordx4 v[152:155], v[192:193], off
	global_load_dwordx4 v[156:159], v[192:193], off offset:16
	global_load_dwordx4 v[160:163], v[194:195], off
	global_load_dwordx4 v[170:173], v[194:195], off offset:16
	global_load_dwordx4 v[174:177], v[196:197], off offset:2048
	global_load_dwordx4 v[178:181], v[196:197], off offset:2064
	global_load_dwordx4 v[182:185], v[198:199], off offset:2048
	global_load_dwordx4 v[186:189], v[198:199], off offset:2064
.Lcw_have:
	s_and_saveexec_b64 s[22:23], s[6:7]
	s_cbranch_execz .Lgate_done
	s_waitcnt vmcnt(0)
	v_mul_f32_e32 v212, 0x3fb8aa3b, v244
	v_fma_f32 v213, v244, s88, -v212
	v_rndne_f32_e32 v214, v212
	v_fmac_f32_e32 v213, 0x32a5705f, v244
	v_sub_f32_e32 v212, v212, v214
	v_add_f32_e32 v212, v212, v213
	v_exp_f32_e32 v212, v212
	v_cvt_i32_f32_e32 v213, v214
	v_cmp_ngt_f32_e32 vcc, s79, v244
	v_ldexp_f32 v212, v212, v213
	s_nop 0
	v_cndmask_b32_e32 v212, 0, v212, vcc
	v_cmp_nlt_f32_e32 vcc, s54, v244
	s_nop 1
	v_cndmask_b32_e32 v80, v210, v212, vcc

; DI void dn_prep_item(const Params& p, int l, int item, int next_item, u32x4 (&pre)[12], unsigned char* lds, int tid) {
;     ...
;         __syncthreads();
;         {
;             const int c = tid & 127, rg = tid >> 7;
;             float xt[32];
; #pragma unroll
;             for (int k = 0; k < 32; ++k) xt[k] = XS[k * 129 + c];
; #pragma unroll
;             for (int ii = 0; ii < 8; ++ii) { const int i = rg * 8 + ii; float a0 = XS[(32 + i) * 129 + c], a1 = 0.f;
; #pragma unroll
;                 for (int k = 0; k < 32; k += 2) { a0 -= Zs[i * 33 + k] * xt[k]; a1 -= Zs[i * 33 + k + 1] * xt[k + 1]; }
;                 XS[(32 + i) * 129 + c] = a0 + a1; }
;         }
;     }
;     __syncthreads();
;     dn_prep_fetch(p, next_item < 2048 ? next_item : item, tid, pre);
.LBB0_503:
	s_or_b64 exec, exec, s[8:9]
	v_ashrrev_i32_e32 v35, 4, v54
	v_and_b32_e32 v2, 0x7f, v54
	v_and_b32_e32 v38, -8, v35
	s_movk_i32 s12, 0x204
	v_lshl_add_u32 v36, v2, 2, v50
	v_mul_lo_u32 v40, v38, s12
	s_movk_i32 s5, 0x84
	v_add_u32_e32 v41, v36, v40
	v_mad_u64_u32 v[38:39], s[6:7], v38, s5, v[52:53]
	s_waitcnt lgkmcnt(0)
	s_barrier
	v_and_b32_e32 v2, 15, v206
	v_lshrrev_b32_e32 v3, 4, v206
	v_lshrrev_b32_e32 v4, 6, v54
	v_lshl_add_u32 v4, v4, 4, v2
	v_mul_u32_u24_e32 v5, 0x90, v2
	v_lshl_add_u32 v5, v3, 2, v5
	v_add_u32_e32 v5, v5, v52
	v_mul_u32_u24_e32 v6, 0x204, v3
	v_lshl_add_u32 v6, v4, 2, v6
	v_add_u32_e32 v6, v6, v50
	v_mul_u32_u24_e32 v7, 0x810, v3
	v_lshl_add_u32 v7, v4, 2, v7
	v_add_u32_e32 v7, v7, v50
	ds_read_b32 v8, v6
	ds_read_b32 v9, v6 offset:2064
	ds_read_b32 v10, v6 offset:4128
	ds_read_b32 v11, v6 offset:6192
	ds_read_b32 v12, v6 offset:8256
	ds_read_b32 v13, v6 offset:10320
	ds_read_b32 v14, v6 offset:12384
	ds_read_b32 v15, v6 offset:14448
	ds_read_b32 v16, v5
	ds_read_b32 v17, v5 offset:16
	ds_read_b32 v18, v5 offset:32
	ds_read_b32 v19, v5 offset:48
	ds_read_b32 v20, v5 offset:64
	ds_read_b32 v21, v5 offset:80
	ds_read_b32 v22, v5 offset:96
	ds_read_b32 v23, v5 offset:112
	ds_read_b32 v24, v5 offset:2304
	ds_read_b32 v25, v5 offset:2320
	ds_read_b32 v26, v5 offset:2336
	ds_read_b32 v27, v5 offset:2352
	ds_read_b32 v28, v5 offset:2368
	ds_read_b32 v29, v5 offset:2384
	ds_read_b32 v30, v5 offset:2400
	ds_read_b32 v31, v5 offset:2416
	ds_read_b32 v36, v7 offset:16512
	ds_read_b32 v37, v7 offset:17028
	ds_read_b32 v38, v7 offset:17544
	ds_read_b32 v39, v7 offset:18060
	ds_read_b32 v40, v7 offset:24768
	ds_read_b32 v41, v7 offset:25284
	ds_read_b32 v42, v7 offset:25800
	ds_read_b32 v43, v7 offset:26316
	s_waitcnt lgkmcnt(8)
	v_mfma_f32_16x16x4_f32 v[44:47], v16, v8, 0
	v_mfma_f32_16x16x4_f32 v[212:215], v24, v8, 0
	v_mfma_f32_16x16x4_f32 v[44:47], v17, v9, v[44:47]
	v_mfma_f32_16x16x4_f32 v[212:215], v25, v9, v[212:215]
	v_mfma_f32_16x16x4_f32 v[44:47], v18, v10, v[44:47]
	v_mfma_f32_16x16x4_f32 v[212:215], v26, v10, v[212:215]
	v_mfma_f32_16x16x4_f32 v[44:47], v19, v11, v[44:47]
	v_mfma_f32_16x16x4_f32 v[212:215], v27, v11, v[212:215]
	v_mfma_f32_16x16x4_f32 v[44:47], v20, v12, v[44:47]
	v_mfma_f32_16x16x4_f32 v[212:215], v28, v12, v[212:215]
	v_mfma_f32_16x16x4_f32 v[44:47], v21, v13, v[44:47]
	v_mfma_f32_16x16x4_f32 v[212:215], v29, v13, v[212:215]
	v_mfma_f32_16x16x4_f32 v[44:47], v22, v14, v[44:47]
	v_mfma_f32_16x16x4_f32 v[212:215], v30, v14, v[212:215]
	v_mfma_f32_16x16x4_f32 v[44:47], v23, v15, v[44:47]
	v_mfma_f32_16x16x4_f32 v[212:215], v31, v15, v[212:215]
	s_waitcnt lgkmcnt(0)
	s_nop 8
	v_sub_f32_e32 v36, v36, v44
	v_sub_f32_e32 v37, v37, v45
	v_sub_f32_e32 v38, v38, v46
	v_sub_f32_e32 v39, v39, v47
	v_sub_f32_e32 v40, v40, v212
	v_sub_f32_e32 v41, v41, v213
	v_sub_f32_e32 v42, v42, v214
	v_sub_f32_e32 v43, v43, v215
	ds_write_b32 v7, v36 offset:16512
	ds_write_b32 v7, v37 offset:17028
	ds_write_b32 v7, v38 offset:17544
	ds_write_b32 v7, v39 offset:18060
	ds_write_b32 v7, v40 offset:24768
	ds_write_b32 v7, v41 offset:25284
	ds_write_b32 v7, v42 offset:25800
	ds_write_b32 v7, v43 offset:26316
	s_add_i32 s4, s42, s33
	s_cmpk_gt_i32 s4, 0x7ff
	v_and_b32_e32 v66, -16, v77
	v_lshl_add_u64 v[62:63], s[26:27], 0, v[58:59]
	v_or_b32_e32 v58, v66, v61
	v_ashrrev_i32_e32 v57, 31, v56
	s_cselect_b64 s[6:7], -1, 0
	s_cmpk_lt_i32 s4, 0x800
	s_cselect_b32 s5, s4, s42
	s_lshl_b32 s8, s5, 3
	s_lshl_b32 s5, s5, 7
	s_and_b32 s10, s8, 0x7c0
	s_and_b32 s11, s8, 0xfffff800
	s_and_b32 s5, s5, 0x380
	s_add_u32 s8, s29, s5
	s_addc_u32 s9, s40, 0
	v_mov_b32_e32 v35, v165
	s_movk_i32 s5, 0xc00
	v_add_u32_e32 v10, s10, v77
	v_max_i32_e32 v10, 0, v10
	v_add_u32_e32 v10, s11, v10
	v_add3_u32 v8, s10, -3, v77
	v_max_i32_e32 v4, 0, v8
	v_max_i32_e32 v6, -1, v8
	v_max_i32_e32 v8, -2, v8
	v_lshl_add_u64 v[2:3], s[8:9], 0, v[34:35]
	v_add_u32_e32 v4, s11, v4
	v_add3_u32 v6, v6, s11, 1
	v_add3_u32 v8, v8, s11, 2
	v_mad_i64_i32 v[4:5], s[8:9], v4, s5, v[2:3]
	v_mad_i64_i32 v[6:7], s[8:9], v6, s5, v[2:3]
	v_mad_i64_i32 v[8:9], s[8:9], v8, s5, v[2:3]
	v_mad_i64_i32 v[2:3], s[8:9], v10, s5, v[2:3]
	s_waitcnt lgkmcnt(0)
	s_barrier
; DI unsigned pk2(float lo, float hi) { f32x2_t v = {lo, hi}; bf16x2_t b = __builtin_convertvector(v, bf16x2_t); return __builtin_bit_cast(unsigned, b); }
; DI void dn_prep_item(const Params& p, int l, int item, int next_item, u32x4 (&pre)[12], unsigned char* lds, int tid) {
;     ...
;                     const f32x4 w0 = *(const f32x4*)(cw + j * 1536 + col), w1 = *(const f32x4*)(cw + j * 1536 + col + 4);
;     ...
;     dn_prep_fetch(p, next_item < 2048 ? next_item : item, tid, pre);
;     {
;         const int chunk = (b * 8 + h) * 32 + n; unsigned char* base = p.ws + OFF_U + (size_t)chunk * PREP_CHUNK_BYTES;
;         const int f = tid >> 6, m = f >> 1, s = f & 1, r = lane & 15, g = lane >> 4, row = 16 * m + r, c0 = 32 * s + 4 * g, c1 = c0 + 16;
;         u32x4 w;
;         { const float* a = XS + row * 129 + 64; w.x = pk2(a[c0], a[c0 + 1]); w.y = pk2(a[c0 + 2], a[c0 + 3]); w.z = pk2(a[c1], a[c1 + 1]); w.w = pk2(a[c1 + 2], a[c1 + 3]); *(u32x4*)(base + (size_t)tid * 16) = w; }
; #pragma unroll
;         for (int q = 0; q < 2; ++q) { const int idx = tid * 2 + q, wm = idx >> 6, ln = idx & 63, vv = 16 * (wm >> 2) + (ln & 15), r0 = 16 * (wm & 3) + 4 * (ln >> 4);
;             u32x2 o; o.x = pk2(XS[r0 * 129 + vv], XS[(r0 + 1) * 129 + vv]); o.y = pk2(XS[(r0 + 2) * 129 + vv], XS[(r0 + 3) * 129 + vv]); *(u32x2*)(base + 32768 + (size_t)idx * 8) = o; }
;         if (tid == 0) ((float*)(p.ws + OFF_CD))[chunk] = EGs[63];
;     }
	global_load_dwordx4 v[46:49], v[4:5], off
	global_load_dwordx4 v[42:45], v[6:7], off
	global_load_dwordx4 v[38:41], v[8:9], off
	global_load_dwordx4 v[34:37], v[2:3], off
	global_load_dwordx4 v[30:33], v[4:5], off offset:1024
	global_load_dwordx4 v[26:29], v[6:7], off offset:1024
	global_load_dwordx4 v[22:25], v[8:9], off offset:1024
	global_load_dwordx4 v[18:21], v[2:3], off offset:1024
	global_load_dwordx4 v[14:17], v[4:5], off offset:2048
	global_load_dwordx4 v[10:13], v[6:7], off offset:2048
	s_nop 0
	global_load_dwordx4 v[6:9], v[8:9], off offset:2048
	s_nop 0
	global_load_dwordx4 v[2:5], v[2:3], off offset:2048
	global_load_dwordx4 v[88:91], v[192:193], off offset:-4080
	global_load_dwordx4 v[92:95], v[192:193], off offset:-4096
	global_load_dwordx4 v[96:99], v[190:191], off
	global_load_dwordx4 v[100:103], v[190:191], off offset:16
	global_load_dwordx4 v[104:107], v[192:193], off offset:2048
	global_load_dwordx4 v[108:111], v[192:193], off offset:2064
	global_load_dwordx4 v[112:115], v[194:195], off offset:2048
	global_load_dwordx4 v[116:119], v[194:195], off offset:2064
	global_load_dwordx4 v[120:123], v[192:193], off offset:-2032
	global_load_dwordx4 v[124:127], v[192:193], off offset:-2048
	global_load_dwordx4 v[128:131], v[190:191], off offset:2048
	global_load_dwordx4 v[132:135], v[190:191], off offset:2064
	global_load_dwordx4 v[136:139], v[196:197], off
	global_load_dwordx4 v[140:143], v[196:197], off offset:16
	global_load_dwordx4 v[144:147], v[198:199], off
	global_load_dwordx4 v[148:151], v[198:199], off offset:16
	global_load_dwordx4 v[152:155], v[192:193], off
	global_load_dwordx4 v[156:159], v[192:193], off offset:16
	global_load_dwordx4 v[160:163], v[194:195], off
	global_load_dwordx4 v[170:173], v[194:195], off offset:16
	global_load_dwordx4 v[174:177], v[196:197], off offset:2048
	global_load_dwordx4 v[178:181], v[196:197], off offset:2064
	global_load_dwordx4 v[182:185], v[198:199], off offset:2048
	global_load_dwordx4 v[186:189], v[198:199], off offset:2064
	v_mad_u64_u32 v[58:59], s[8:9], v58, s12, v[50:51]
	v_lshlrev_b32_e32 v59, 7, v60
	v_and_b32_e32 v59, 0x80, v59
	v_and_b32_e32 v60, 48, v54
	v_add3_u32 v64, v58, v59, v60
	ds_read2_b32 v[58:59], v64 offset0:64 offset1:65
	ds_read2_b32 v[60:61], v64 offset0:66 offset1:67
	s_waitcnt lgkmcnt(1)
	v_cvt_pk_bf16_f32 v58, v58, v59
	s_waitcnt lgkmcnt(0)
	v_cvt_pk_bf16_f32 v59, v60, v61
	ds_read2_b32 v[60:61], v64 offset0:80 offset1:81
	ds_read2_b32 v[64:65], v64 offset0:82 offset1:83
	s_waitcnt lgkmcnt(1)
	v_cvt_pk_bf16_f32 v60, v60, v61
	s_waitcnt lgkmcnt(0)
	v_cvt_pk_bf16_f32 v61, v64, v65
	v_lshl_add_u64 v[64:65], v[54:55], 4, v[62:63]
	v_lshrrev_b32_e32 v55, 1, v54
	global_store_dwordx4 v[64:65], v[58:61], off
	v_and_b32_e32 v55, 48, v55
	s_nop 0
	v_lshrrev_b32_e32 v58, 2, v56
	v_and_or_b32 v55, v58, 12, v55
	v_mul_u32_u24_e32 v55, 0x81, v55
	v_and_b32_e32 v58, 14, v56
	v_lshl_add_u32 v58, v58, 2, v50
	v_lshlrev_b32_e32 v59, 2, v66
	v_lshlrev_b32_e32 v55, 2, v55
	v_add3_u32 v55, v58, v59, v55
	ds_read2_b32 v[60:61], v55 offset1:1
	ds_read2_b32 v[64:65], v55 offset0:129 offset1:130
	v_add_u32_e32 v59, 0x408, v55
	v_add_u32_e32 v55, 0x60c, v55
	ds_read2_b32 v[66:67], v59 offset1:1
	ds_read2_b32 v[78:79], v55 offset1:1
	v_lshl_add_u64 v[56:57], v[56:57], 3, v[62:63]
	v_add_co_u32_e32 v56, vcc, 0x8000, v56
	s_waitcnt lgkmcnt(2)
	v_cvt_pk_bf16_f32 v58, v60, v64
	v_addc_co_u32_e32 v57, vcc, 0, v57, vcc
	s_waitcnt lgkmcnt(0)
	v_cvt_pk_bf16_f32 v59, v66, v78
	v_cvt_pk_bf16_f32 v60, v61, v65
	v_cvt_pk_bf16_f32 v61, v67, v79
	v_cmp_eq_u32_e32 vcc, 0, v54
	global_store_dwordx4 v[56:57], v[58:61], off
	s_and_saveexec_b64 s[8:9], vcc
	s_cbranch_execz .LBB0_280
	ds_read_b32 v54, v76
	v_lshl_add_u64 v[0:1], v[0:1], 2, s[38:39]
	s_waitcnt lgkmcnt(0)
	global_store_dword v[0:1], v54, off
	s_branch .LBB0_280
